# Fourier step-1 unit order: cos/sin halves of one tile on the same XCD (shared z tile in L2)
# speedup vs baseline: 1.0074x; 1.0074x over previous
.LBB0_78:
	s_or_b64 exec, exec, s[0:1]
	s_add_u32 s18, s94, 0x752c000
	s_addc_u32 s19, s95, 0
	s_add_u32 s8, s94, 0x652c000
	s_addc_u32 s73, s95, 0
	s_add_u32 s1, s94, 0x64ec000
	s_addc_u32 s2, s95, 0
	s_add_u32 s0, s94, 0x34590000
	v_writelane_b32 v252, s0, 28
	s_addc_u32 s0, s95, 0
	v_writelane_b32 v252, s0, 29
	s_lshl_b32 s0, s92, 3
	s_lshl_b32 s88, s30, 3
	v_writelane_b32 v252, s0, 30
	s_add_u32 s0, s94, 0x6480000
	v_writelane_b32 v252, s0, 31
	s_addc_u32 s0, s95, 0
	s_add_u32 s96, s94, 0x756c000
	s_addc_u32 s97, s95, 0
	s_cmpk_lt_i32 s92, 0x780
	v_writelane_b32 v252, s0, 32
	s_cselect_b64 s[4:5], -1, 0
	v_writelane_b32 v252, s4, 33
	s_add_u32 s17, s74, 0x7800000
	s_mov_b64 s[20:21], src_shared_base
	v_writelane_b32 v252, s5, 34
	v_writelane_b32 v252, s60, 35
	s_addc_u32 s20, s75, 0
	s_add_u32 s4, s94, 0x35592000
	v_writelane_b32 v252, s61, 36
	v_writelane_b32 v252, s62, 37
	v_writelane_b32 v252, s63, 38
	v_writelane_b32 v252, s64, 39
	v_writelane_b32 v252, s65, 40
	v_writelane_b32 v252, s66, 41
	v_writelane_b32 v252, s67, 42
	v_writelane_b32 v252, s68, 43
	v_writelane_b32 v252, s69, 44
	v_writelane_b32 v252, s70, 45
	v_writelane_b32 v252, s71, 46
	v_writelane_b32 v252, s72, 47
	v_writelane_b32 v252, s73, 48
	v_writelane_b32 v252, s74, 49
	s_addc_u32 s5, s95, 0
	v_writelane_b32 v252, s75, 50
	s_add_u32 s50, s94, 0xbd6c000
	v_writelane_b32 v252, s4, 51
	s_addc_u32 s51, s95, 0
	s_mov_b32 s43, 0
	v_writelane_b32 v252, s5, 52
	s_add_u32 s4, s94, 0x2916c000
	s_addc_u32 s5, s95, 0
	v_writelane_b32 v252, s4, 53
	s_mul_i32 s26, s30, 0x34000
	s_mul_hi_i32 s27, s88, 0x6800
	v_writelane_b32 v252, s5, 54
	s_add_u32 s4, s94, 0x2b56c000
	s_addc_u32 s5, s95, 0
	v_writelane_b32 v252, s4, 55
	v_mov_b32_e32 v195, 0
	v_mov_b32_e32 v230, 0x358637bd
	v_writelane_b32 v252, s5, 56
	s_and_b32 s4, s92, 7
	s_or_b32 s0, s4, 24
	v_writelane_b32 v252, s0, 57
	s_lshr_b32 s0, s93, 29
	s_add_i32 s0, s92, s0
	s_mov_b32 s93, s1
	s_ashr_i32 s1, s0, 3
	s_and_b32 s0, s0, -8
	v_writelane_b32 v252, s1, 58
	s_sub_i32 s0, s92, s0
	v_writelane_b32 v252, s0, 59
	s_lshr_b32 s0, s0, 31
	s_add_u32 s64, s94, 0xb56c000
	v_writelane_b32 v252, s0, 60
	s_addc_u32 s65, s95, 0
	s_ashr_i32 s5, s92, 3
	s_and_b32 s0, s92, 1
	s_bfe_u32 s3, s92, 0x10003
	s_xor_b32 s0, s0, s3
	s_lshl_b32 s3, s0, 3
	s_or_b32 s0, s0, s3
	s_xor_b32 s1, s92, s0
	s_and_b32 s0, s1, 1
	s_bfe_u32 s3, s1, 0x20001
	s_ashr_i32 s1, s1, 3
	s_nop 0
	v_writelane_b32 v251, s1, 16
	v_writelane_b32 v252, s0, 61
	s_lshl_b32 s0, s0, 17
	s_add_u32 s6, s93, s0
	v_writelane_b32 v252, s2, 62
	s_addc_u32 s7, s2, 0
	s_mul_i32 s0, s1, 0x340000
	v_writelane_b32 v252, s3, 63
	s_lshl_b32 s3, s3, 8
	s_mul_hi_i32 s1, s1, 0x340000
	s_or_b32 s0, s0, s3
	s_lshl_b64 s[0:1], s[0:1], 1
	s_add_u32 s0, s50, s0
	s_addc_u32 s1, s51, s1
	s_add_u32 s2, s0, 0x1000
	s_addc_u32 s3, s1, 0
	v_writelane_b32 v251, s2, 0
	v_mov_b32_e32 v196, 0x20000
	v_mov_b32_e32 v231, 1
	v_writelane_b32 v251, s3, 1
	s_add_u32 s2, s0, 0x341000
	s_addc_u32 s3, s1, 0
	v_writelane_b32 v251, s2, 2
	v_mov_b32_e32 v232, 7
	v_mov_b32_e32 v198, 0x20010
	v_writelane_b32 v251, s3, 3
	s_add_u32 s2, s6, 0x10000
	v_writelane_b32 v251, s6, 4
	s_addc_u32 s3, s7, 0
	v_mov_b32_e32 v241, 0x400
	v_writelane_b32 v251, s7, 5
	v_writelane_b32 v251, s2, 6
	v_mov_b32_e32 v200, 0x20008
	v_mov_b32_e32 v202, 0x2000c
	v_writelane_b32 v251, s3, 7
	s_add_u32 s2, s0, 0x1080
	s_addc_u32 s3, s1, 0
	v_writelane_b32 v251, s2, 8
	s_add_u32 s0, s0, 0x341080
	s_addc_u32 s1, s1, 0
	v_writelane_b32 v251, s3, 9
	v_writelane_b32 v251, s0, 10
	v_mov_b32_e32 v204, 0x20004
	v_mov_b32_e32 v205, s21
	v_writelane_b32 v251, s1, 11
	s_add_u32 s0, s94, 0x2d96c000
	s_addc_u32 s1, s95, 0
	s_add_u32 s74, s94, 0x2fd90000
	s_addc_u32 s75, s95, 0
	v_writelane_b32 v251, s0, 12
	s_cmpk_lt_i32 s92, 0x100
	s_movk_i32 s37, 0x6800
	v_writelane_b32 v251, s1, 13
	s_cselect_b64 s[0:1], -1, 0
	v_writelane_b32 v251, s0, 14
	s_movk_i32 s16, 0x1000
	s_mov_b32 s70, 0x800000
	v_writelane_b32 v251, s1, 15
	s_and_b32 s0, s5, -8
	s_or_b32 s2, s0, s4
	s_bfe_u32 s0, s92, 0x30003
	v_writelane_b32 v251, s0, 17
	s_lshl_b32 s0, s0, 21
	v_writelane_b32 v251, s8, 18
	s_add_u32 s4, s8, s0
	s_mov_b32 s0, s2
	s_addc_u32 s5, s73, 0
	s_ashr_i32 s3, s2, 31
	v_writelane_b32 v251, s0, 19
	s_mov_b32 s25, 0xf000
	s_movk_i32 s33, 0x204
	v_writelane_b32 v251, s1, 20
	s_lshl_b64 s[0:1], s[2:3], 21
	s_add_u32 s0, s96, s0
	s_addc_u32 s1, s97, s1
	s_add_u32 s2, s0, 0x100000
	s_addc_u32 s3, s1, 0
	v_writelane_b32 v251, s2, 21
	s_mov_b32 s34, 0x5040100
	s_movk_i32 s91, 0x2000
	v_writelane_b32 v251, s3, 22
	s_add_u32 s2, s4, 0x100000
	v_writelane_b32 v251, s4, 23
	s_addc_u32 s3, s5, 0
	s_mov_b32 s44, 0x90000
	v_writelane_b32 v251, s5, 24
	v_writelane_b32 v251, s2, 25
	s_mov_b32 s45, 0x120000
	s_mov_b32 s90, 0x1b0000
	v_writelane_b32 v251, s3, 26
	s_add_u32 s2, s0, 0x100080
	v_writelane_b32 v251, s0, 27
	s_addc_u32 s3, s1, 0
	s_mov_b32 s46, 0x2d0000
	v_writelane_b32 v251, s1, 28
	v_writelane_b32 v251, s2, 29
	s_add_i32 s0, s92, 0x80
	s_mov_b32 s47, 0x360000
	v_writelane_b32 v251, s3, 30
	s_add_u32 s2, s94, 0x754c000
	s_addc_u32 s3, s95, 0
	v_writelane_b32 v251, s2, 31
	s_mov_b32 s31, 0x3f0000
	s_mov_b64 s[76:77], 0x80
	v_writelane_b32 v251, s3, 32
	s_add_u32 s2, s94, 0x752c080
	s_addc_u32 s3, s95, 0
	v_writelane_b32 v251, s2, 33
	s_mov_b64 s[84:85], 0x1800
	s_mov_b32 s72, 0x3ab504f3
	v_writelane_b32 v251, s3, 34
	s_add_u32 s2, s94, 0x2d990000
	s_addc_u32 s3, s95, 0
	s_add_u32 s28, s94, 0x32190000
	v_writelane_b32 v251, s2, 35
	s_addc_u32 s29, s95, 0
	s_add_u32 s1, s94, 0x3c00000
	v_writelane_b32 v251, s3, 36
	v_writelane_b32 v251, s1, 37
	s_addc_u32 s1, s95, 0
	v_writelane_b32 v251, s1, 38
	s_add_u32 s1, s94, 0x5400000
	v_writelane_b32 v251, s1, 39
	s_addc_u32 s1, s95, 0
	v_writelane_b32 v251, s1, 40
	s_abs_i32 s1, s30
	v_cvt_f32_u32_e32 v2, s1
	s_sub_i32 s3, 0, s1
	s_mov_b32 s36, 0x3b800000
	s_mov_b64 s[68:69], 0x2800
	v_rcp_iflag_f32_e32 v2, v2
	s_mov_b64 s[38:39], 0x3800
	v_mul_f32_e32 v2, 0x4f7ffffe, v2
	v_cvt_u32_f32_e32 v2, v2
	s_nop 0
	v_readfirstlane_b32 s4, v2
	s_mul_i32 s3, s3, s4
	s_mul_hi_u32 s3, s4, s3
	s_add_i32 s4, s4, s3
	s_abs_i32 s3, s0
	s_mul_hi_u32 s4, s3, s4
	s_mul_i32 s4, s4, s1
	s_sub_i32 s3, s3, s4
	s_ashr_i32 s0, s0, 31
	s_sub_i32 s4, s3, s1
	s_cmp_ge_u32 s3, s1
	s_cselect_b32 s3, s4, s3
	s_sub_i32 s4, s3, s1
	s_cmp_ge_u32 s3, s1
	s_cselect_b32 s1, s4, s3
	s_xor_b32 s1, s1, s0
	s_sub_i32 s2, s1, s0
	s_cmp_lt_i32 s2, 32
	s_cselect_b64 s[0:1], -1, 0
	v_writelane_b32 v251, s0, 41
	s_ashr_i32 s3, s2, 31
	v_mbcnt_lo_u32_b32 v2, -1, 0
	v_writelane_b32 v251, s1, 42
	s_mov_b32 s0, s2
	v_writelane_b32 v251, s0, 43
	v_mbcnt_hi_u32_b32 v233, -1, v2
	v_and_b32_e32 v2, 64, v233
	v_writelane_b32 v251, s1, 44
	s_lshl_b64 s[0:1], s[2:3], 18
	s_add_u32 s0, s64, s0
	s_addc_u32 s1, s65, s1
	s_add_u32 s2, s0, 0x20000
	s_addc_u32 s3, s1, 0
	v_writelane_b32 v251, s2, 45
	v_add_u32_e32 v234, 64, v2
	v_xor_b32_e32 v235, 32, v233
	v_writelane_b32 v251, s3, 46
	s_add_u32 s2, s0, 0x20080
	v_writelane_b32 v251, s0, 47
	s_addc_u32 s3, s1, 0
	s_ashr_i32 s89, s88, 31
	v_writelane_b32 v251, s1, 48
	v_writelane_b32 v251, s2, 49
	s_lshl_b32 s0, s92, 8
	s_lshl_b32 s24, s30, 8
	v_writelane_b32 v251, s3, 50
	v_writelane_b32 v251, s0, 51
	s_lshl_b64 s[0:1], s[88:89], 13
	v_writelane_b32 v251, s0, 52
	v_xor_b32_e32 v236, 16, v233
	v_xor_b32_e32 v237, 8, v233
	v_writelane_b32 v251, s1, 53
	s_add_u32 s0, s94, 0xbd6e800
	s_addc_u32 s1, s95, 0
	v_writelane_b32 v251, s0, 54
	s_lshl_b32 s66, s30, 6
	v_xor_b32_e32 v238, 4, v233
	v_writelane_b32 v251, s1, 55
	s_lshl_b32 s0, s92, 6
	v_writelane_b32 v251, s0, 56
	s_add_u32 s0, s94, 0x754c080
	s_addc_u32 s1, s95, 0
	v_writelane_b32 v251, s0, 57
	v_xor_b32_e32 v239, 2, v233
	v_xor_b32_e32 v240, 1, v233
	v_writelane_b32 v251, s1, 58
	s_lshl_b32 s0, s92, 5
	v_writelane_b32 v251, s0, 59
	s_lshl_b32 s0, s30, 5
	v_writelane_b32 v251, s0, 60
	v_readlane_b32 s0, v252, 12
	v_readlane_b32 s6, v252, 18
	v_readlane_b32 s1, v252, 13
	v_readlane_b32 s7, v252, 19
	s_add_u32 s0, s6, 64
	s_addc_u32 s1, s7, 0
	v_writelane_b32 v251, s0, 61
	v_readlane_b32 s2, v252, 14
	v_readlane_b32 s3, v252, 15
	v_writelane_b32 v251, s1, 62
	s_lshl_b32 s0, s92, 7
	v_writelane_b32 v251, s0, 63
	s_lshl_b32 s0, s92, 4
	v_writelane_b32 v250, s0, 0
	s_lshl_b32 s0, s30, 4
	v_writelane_b32 v250, s0, 1
	s_mov_b32 s0, s43
	v_writelane_b32 v250, s0, 2
	s_lshl_b32 s79, s30, 7
	s_mov_b64 s[2:3], -1
	v_writelane_b32 v250, s1, 3
	v_writelane_b32 v250, s94, 4
	s_mov_b32 s1, s21
	v_readlane_b32 s4, v252, 16
	v_writelane_b32 v250, s95, 5
	v_writelane_b32 v250, s17, 6
	v_writelane_b32 v250, s20, 7
	v_writelane_b32 v250, s64, 8
	v_readlane_b32 s5, v252, 17
	v_readlane_b32 s8, v252, 20
	v_writelane_b32 v250, s65, 9
	v_writelane_b32 v250, s0, 10
	v_readlane_b32 s9, v252, 21
	v_readlane_b32 s10, v252, 22
	v_writelane_b32 v250, s1, 11
	v_writelane_b32 v250, s28, 12
	v_readlane_b32 s11, v252, 23
	v_readlane_b32 s12, v252, 24
	v_writelane_b32 v250, s29, 13
	v_writelane_b32 v250, s24, 14
	v_writelane_b32 v250, s26, 15
	v_readlane_b32 s13, v252, 25
	v_readlane_b32 s14, v252, 26
	v_writelane_b32 v250, s27, 16
	v_writelane_b32 v250, s66, 17
	v_readlane_b32 s15, v252, 27
	v_writelane_b32 v250, s79, 18
	s_branch .LBB0_81

.LBB0_201:
	s_add_i32 s79, s79, 1
	s_mul_i32 s8, s79, s30
	s_add_i32 s8, s8, s92
	s_cmp_ge_i32 s8, s33
	s_cselect_b64 s[40:41], -1, 0
	s_and_b64 vcc, exec, s[40:41]
	s_cbranch_vccnz .LBB0_203
	s_and_b32 s95, s8, 1
	s_bfe_u32 s86, s8, 0x10003
	s_xor_b32 s95, s95, s86
	s_lshl_b32 s86, s95, 3
	s_or_b32 s95, s95, s86
	s_xor_b32 s28, s8, s95
	s_and_b32 s95, s28, 1
	s_bfe_u32 s86, s28, 0x20001
	s_ashr_i32 s28, s28, 3
	s_lshl_b32 s0, s95, 17
	s_add_u32 s0, s93, s0
	s_addc_u32 s1, s2, 0
	s_mul_i32 s6, s28, 0x340000
	s_lshl_b32 s8, s86, 8
	s_mul_hi_i32 s7, s28, 0x340000
	s_or_b32 s6, s6, s8
	s_lshl_b64 s[6:7], s[6:7], 1
	s_add_u32 s6, s50, s6
	s_addc_u32 s7, s51, s7
	s_add_u32 s6, s6, 0x1000
	s_addc_u32 s7, s7, 0
